# v22 + hand-written FFN-up (SwiGLU) epilogue: precomputed offsets, no per-combo dispatch, IEEE division Newton steps as packed f32 on element pairs (same arithmetic)
# speedup vs baseline: 1.0127x; 1.0127x over previous
; #define PG8_STAGE(bufoff, gbase, voff) do { _Pragma("unroll") for (int _i = 0; _i < 2; ++_i) \
;     __builtin_amdgcn_global_load_lds((const unsigned*)((const char*)(gbase) + (voff)[_i]), (LAS unsigned*)(lds + (bufoff) + ldsw + _i * 8192), 16, 0, 0); } while (0)
; #define PG8_LDA(dst, b, h) do { _Pragma("unroll") for (int m = 0; m < 4; ++m) _Pragma("unroll") for (int k = 0; k < 2; ++k) dst[m][k] = *(const LAS bf16x8*)(lds + PG8_SA(b, h) + aoff + m * 2048 + k * 1024); } while (0)
; #define PG8_LDB(dst, b, h) do { _Pragma("unroll") for (int n = 0; n < 2; ++n) _Pragma("unroll") for (int k = 0; k < 2; ++k) dst[n][k] = *(const LAS bf16x8*)(lds + PG8_SB(b, h) + boff + n * 2048 + k * 1024); } while (0)
; #define PG8_MMA(ai, bj, At, Bt) do { __builtin_amdgcn_s_setprio(1); _Pragma("unroll") for (int m = 0; m < 4; ++m) _Pragma("unroll") for (int n = 0; n < 2; ++n) _Pragma("unroll") for (int k = 0; k < 2; ++k) \
;     acc[ai][bj][m][n] = __builtin_amdgcn_mfma_f32_16x16x32_bf16(Bt[n][k], At[m][k], acc[ai][bj][m][n], 0, 0, 0); __builtin_amdgcn_s_setprio(0); } while (0)
; #define PG8_WAIT_L(n) asm volatile("s_waitcnt lgkmcnt(" #n ")" ::: "memory")
; #define PG8_BAR __builtin_amdgcn_s_barrier()
; #define PG8_SCHED __builtin_amdgcn_sched_barrier(0)
; template <class Epi>
; __device__ __forceinline__ void gemm_phase(LAS unsigned char* lds, const Gemm g, const Epi& E) {
;     ...
;     for (int t = 0; t < nt; t += 2) {
;       const bool last = (t == nt - 2);
;       const char* a1 = cA + (size_t)(t + 1) * kstep;
;       const char* a2 = last ? nA : cA + (size_t)(t + 2) * kstep; const char* b2 = last ? nB : cB + (size_t)(t + 2) * kstep;
;       const char* a3 = a2 + kstep; const char* b3 = b2 + kstep;
;       PG8_LDB(B0, 0, 0); PG8_SCHED; PG8_LDA(At, 0, 0); PG8_STAGE(PG8_SA(1, 1), a1 + hstepA, voffA);
;       PG8_WAIT_L(8); PG8_BAR; PG8_WAIT_L(0); PG8_MMA(0, 0, At, B0); PG8_BAR; PG8_SCHED;
;       PG8_LDB(B1, 0, 1); PG8_STAGE(PG8_SB(0, 0), b2, voffB);
;       PG8_BAR; PG8_WAIT_L(0); PG8_MMA(0, 1, At, B1); PG8_BAR;
;       PG8_LDA(At, 0, 1); PG8_STAGE(PG8_SA(0, 0), a2, voffA);
;       PG8_BAR; PG8_WAIT_L(0); PG8_MMA(1, 0, At, B0); PG8_BAR; PG8_SCHED;
.LBB0_579:
	s_add_i32 s76, s26, 2
	s_add_u32 s28, s2, 0x80
	s_addc_u32 s27, s3, 0
	s_add_i32 s83, 0, 0x10000
	v_add_u32_e32 v156, s83, v173
	ds_read_b128 v[128:131], v156
	ds_read_b128 v[148:151], v156 offset:1024
	ds_read_b128 v[152:155], v156 offset:2048
	ds_read_b128 v[156:159], v156 offset:3072
	s_cmp_eq_u32 s89, s26
	s_cselect_b32 s26, s0, s28
	s_cselect_b32 s27, s1, s27
	s_cselect_b32 s29, s21, s39
	s_cselect_b32 s28, s20, s38
	v_lshl_add_u64 v[196:197], s[2:3], 0, v[144:145]
	s_add_i32 m0, s84, 0xc000
	ds_read_b128 v[160:163], v175
	ds_read_b128 v[164:167], v175 offset:1024
	ds_read_b128 v[168:171], v175 offset:2048
	ds_read_b128 v[176:179], v175 offset:3072
	ds_read_b128 v[180:183], v175 offset:4096
	ds_read_b128 v[184:187], v175 offset:5120
	ds_read_b128 v[188:191], v175 offset:6144
	ds_read_b128 v[192:195], v175 offset:7168
	global_load_lds_dwordx4 v[196:197], off
	v_lshl_add_u64 v[196:197], s[2:3], 0, v[146:147]
	s_add_i32 m0, s84, 0xe000
	s_nop 0
	global_load_lds_dwordx4 v[196:197], off
	s_waitcnt lgkmcnt(8)
	s_barrier
	s_waitcnt lgkmcnt(0)
	s_setprio 1
	s_waitcnt lgkmcnt(0)
	v_mfma_f32_16x16x32_bf16 v[124:127], v[128:131], v[160:163], v[124:127]
	v_mfma_f32_16x16x32_bf16 v[120:123], v[152:155], v[160:163], v[120:123]
	v_mfma_f32_16x16x32_bf16 v[108:111], v[128:131], v[168:171], v[108:111]
	v_mfma_f32_16x16x32_bf16 v[104:107], v[152:155], v[168:171], v[104:107]
	v_mfma_f32_16x16x32_bf16 v[92:95], v[128:131], v[180:183], v[92:95]
	v_mfma_f32_16x16x32_bf16 v[88:91], v[152:155], v[180:183], v[88:91]
	v_mfma_f32_16x16x32_bf16 v[76:79], v[128:131], v[188:191], v[76:79]
	v_mfma_f32_16x16x32_bf16 v[72:75], v[152:155], v[188:191], v[72:75]
	v_mfma_f32_16x16x32_bf16 v[124:127], v[148:151], v[164:167], v[124:127]
	v_mfma_f32_16x16x32_bf16 v[120:123], v[156:159], v[164:167], v[120:123]
	v_mfma_f32_16x16x32_bf16 v[108:111], v[148:151], v[176:179], v[108:111]
	v_mfma_f32_16x16x32_bf16 v[104:107], v[156:159], v[176:179], v[104:107]
	v_mfma_f32_16x16x32_bf16 v[92:95], v[148:151], v[184:187], v[92:95]
	v_mfma_f32_16x16x32_bf16 v[88:91], v[156:159], v[184:187], v[88:91]
	v_mfma_f32_16x16x32_bf16 v[76:79], v[148:151], v[192:195], v[76:79]
	v_mfma_f32_16x16x32_bf16 v[72:75], v[156:159], v[192:195], v[72:75]
	s_setprio 0
	s_barrier
	s_add_i32 s94, 0, 0x14000
	s_add_i32 s83, s83, s97
	v_add_u32_e32 v208, s94, v173
	v_lshl_add_u64 v[212:213], s[28:29], 0, v[132:133]
	s_mov_b32 m0, s83
	ds_read_b128 v[196:199], v208
	ds_read_b128 v[200:203], v208 offset:1024
	ds_read_b128 v[204:207], v208 offset:2048
	ds_read_b128 v[208:211], v208 offset:3072
	global_load_lds_dwordx4 v[212:213], off
	v_lshl_add_u64 v[214:215], s[28:29], 0, v[142:143]
	s_add_i32 m0, s83, 0x2000
	s_nop 0
	global_load_lds_dwordx4 v[214:215], off
	s_barrier
	s_waitcnt lgkmcnt(0)
	s_setprio 1
	s_waitcnt lgkmcnt(0)
	v_mfma_f32_16x16x32_bf16 v[116:119], v[196:199], v[160:163], v[116:119]
	v_mfma_f32_16x16x32_bf16 v[112:115], v[204:207], v[160:163], v[112:115]
	v_mfma_f32_16x16x32_bf16 v[100:103], v[196:199], v[168:171], v[100:103]
	v_mfma_f32_16x16x32_bf16 v[96:99], v[204:207], v[168:171], v[96:99]
	v_mfma_f32_16x16x32_bf16 v[84:87], v[196:199], v[180:183], v[84:87]
	v_mfma_f32_16x16x32_bf16 v[80:83], v[204:207], v[180:183], v[80:83]
	v_mfma_f32_16x16x32_bf16 v[68:71], v[196:199], v[188:191], v[68:71]
	v_mfma_f32_16x16x32_bf16 v[64:67], v[204:207], v[188:191], v[64:67]
	v_mfma_f32_16x16x32_bf16 v[116:119], v[200:203], v[164:167], v[116:119]
	v_mfma_f32_16x16x32_bf16 v[112:115], v[208:211], v[164:167], v[112:115]
	v_mfma_f32_16x16x32_bf16 v[100:103], v[200:203], v[176:179], v[100:103]
	v_mfma_f32_16x16x32_bf16 v[96:99], v[208:211], v[176:179], v[96:99]
	v_mfma_f32_16x16x32_bf16 v[84:87], v[200:203], v[184:187], v[84:87]
	v_mfma_f32_16x16x32_bf16 v[80:83], v[208:211], v[184:187], v[80:83]
	v_mfma_f32_16x16x32_bf16 v[68:71], v[200:203], v[192:195], v[68:71]
	v_mfma_f32_16x16x32_bf16 v[64:67], v[208:211], v[192:195], v[64:67]
	s_setprio 0
	s_mov_b32 m0, s84
	v_lshl_add_u64 v[216:217], s[26:27], 0, v[138:139]
	s_barrier
	ds_read_b128 v[160:163], v175 offset:16384
	ds_read_b128 v[164:167], v175 offset:17408
	ds_read_b128 v[168:171], v175 offset:18432
	ds_read_b128 v[176:179], v175 offset:19456
	ds_read_b128 v[180:183], v175 offset:20480
	ds_read_b128 v[184:187], v175 offset:21504
	ds_read_b128 v[188:191], v175 offset:22528
	ds_read_b128 v[192:195], v175 offset:23552
	global_load_lds_dwordx4 v[216:217], off
	v_lshl_add_u64 v[218:219], s[26:27], 0, v[140:141]
	s_mov_b32 m0, s85
	s_nop 0
	global_load_lds_dwordx4 v[218:219], off
	s_barrier
	s_waitcnt lgkmcnt(0)
	s_setprio 1
	s_waitcnt lgkmcnt(0)
	v_mfma_f32_16x16x32_bf16 v[60:63], v[128:131], v[160:163], v[60:63]
	v_mfma_f32_16x16x32_bf16 v[56:59], v[152:155], v[160:163], v[56:59]
	v_mfma_f32_16x16x32_bf16 v[44:47], v[128:131], v[168:171], v[44:47]
	v_mfma_f32_16x16x32_bf16 v[40:43], v[152:155], v[168:171], v[40:43]
	v_mfma_f32_16x16x32_bf16 v[28:31], v[128:131], v[180:183], v[28:31]
	v_mfma_f32_16x16x32_bf16 v[24:27], v[152:155], v[180:183], v[24:27]
	v_mfma_f32_16x16x32_bf16 v[12:15], v[128:131], v[188:191], v[12:15]
	v_mfma_f32_16x16x32_bf16 v[8:11], v[152:155], v[188:191], v[8:11]
	v_mfma_f32_16x16x32_bf16 v[60:63], v[148:151], v[164:167], v[60:63]
	v_mfma_f32_16x16x32_bf16 v[56:59], v[156:159], v[164:167], v[56:59]
	v_mfma_f32_16x16x32_bf16 v[44:47], v[148:151], v[176:179], v[44:47]
	v_mfma_f32_16x16x32_bf16 v[40:43], v[156:159], v[176:179], v[40:43]
	v_mfma_f32_16x16x32_bf16 v[28:31], v[148:151], v[184:187], v[28:31]
	v_mfma_f32_16x16x32_bf16 v[24:27], v[156:159], v[184:187], v[24:27]
	v_mfma_f32_16x16x32_bf16 v[12:15], v[148:151], v[192:195], v[12:15]
	v_mfma_f32_16x16x32_bf16 v[8:11], v[156:159], v[192:195], v[8:11]
	s_setprio 0
	s_barrier
; #define PG8_STAGE(bufoff, gbase, voff) do { _Pragma("unroll") for (int _i = 0; _i < 2; ++_i) \
;     __builtin_amdgcn_global_load_lds((const unsigned*)((const char*)(gbase) + (voff)[_i]), (LAS unsigned*)(lds + (bufoff) + ldsw + _i * 8192), 16, 0, 0); } while (0)
; #define PG8_LDA(dst, b, h) do { _Pragma("unroll") for (int m = 0; m < 4; ++m) _Pragma("unroll") for (int k = 0; k < 2; ++k) dst[m][k] = *(const LAS bf16x8*)(lds + PG8_SA(b, h) + aoff + m * 2048 + k * 1024); } while (0)
; #define PG8_LDB(dst, b, h) do { _Pragma("unroll") for (int n = 0; n < 2; ++n) _Pragma("unroll") for (int k = 0; k < 2; ++k) dst[n][k] = *(const LAS bf16x8*)(lds + PG8_SB(b, h) + boff + n * 2048 + k * 1024); } while (0)
; #define PG8_MMA(ai, bj, At, Bt) do { __builtin_amdgcn_s_setprio(1); _Pragma("unroll") for (int m = 0; m < 4; ++m) _Pragma("unroll") for (int n = 0; n < 2; ++n) _Pragma("unroll") for (int k = 0; k < 2; ++k) \
;     acc[ai][bj][m][n] = __builtin_amdgcn_mfma_f32_16x16x32_bf16(Bt[n][k], At[m][k], acc[ai][bj][m][n], 0, 0, 0); __builtin_amdgcn_s_setprio(0); } while (0)
; #define PG8_WAIT_V(n) asm volatile("s_waitcnt vmcnt(" #n ")" ::: "memory")
; #define PG8_WAIT_L(n) asm volatile("s_waitcnt lgkmcnt(" #n ")" ::: "memory")
; #define PG8_BAR __builtin_amdgcn_s_barrier()
; #define PG8_SCHED __builtin_amdgcn_sched_barrier(0)
; template <class Epi>
; __device__ __forceinline__ void gemm_phase(LAS unsigned char* lds, const Gemm g, const Epi& E) {
;     ...
;       PG8_STAGE(PG8_SB(0, 1), b2 + hstepB, voffB);
;       PG8_WAIT_V(6); PG8_BAR; PG8_MMA(1, 1, At, B1); PG8_BAR;
;       PG8_LDB(B0, 1, 0); PG8_SCHED; PG8_LDA(At, 1, 0); PG8_STAGE(PG8_SA(0, 1), a2 + hstepA, voffA);
;       PG8_WAIT_L(8); PG8_BAR; PG8_WAIT_L(0); PG8_MMA(0, 0, At, B0); PG8_BAR; PG8_SCHED;
;       PG8_LDB(B1, 1, 1); PG8_STAGE(PG8_SB(1, 0), b3, voffB);
;       PG8_BAR; PG8_WAIT_L(0); PG8_MMA(0, 1, At, B1); PG8_BAR;
	s_add_u32 s28, s28, s95
	s_addc_u32 s29, s29, 0
	s_add_i32 s83, s94, s97
	v_lshl_add_u64 v[220:221], s[28:29], 0, v[132:133]
	s_mov_b32 m0, s83
	v_lshl_add_u64 v[222:223], s[28:29], 0, v[142:143]
	global_load_lds_dwordx4 v[220:221], off
	s_add_i32 m0, s83, 0x2000
	s_nop 0
	global_load_lds_dwordx4 v[222:223], off
	s_waitcnt vmcnt(6)
	s_barrier
	s_setprio 1
	v_mfma_f32_16x16x32_bf16 v[52:55], v[196:199], v[160:163], v[52:55]
	v_mfma_f32_16x16x32_bf16 v[48:51], v[204:207], v[160:163], v[48:51]
	v_mfma_f32_16x16x32_bf16 v[36:39], v[196:199], v[168:171], v[36:39]
	v_mfma_f32_16x16x32_bf16 v[32:35], v[204:207], v[168:171], v[32:35]
	v_mfma_f32_16x16x32_bf16 v[20:23], v[196:199], v[180:183], v[20:23]
	v_mfma_f32_16x16x32_bf16 v[16:19], v[204:207], v[180:183], v[16:19]
	v_mfma_f32_16x16x32_bf16 v[4:7], v[196:199], v[188:191], v[4:7]
	v_mfma_f32_16x16x32_bf16 v[0:3], v[204:207], v[188:191], v[0:3]
	v_mfma_f32_16x16x32_bf16 v[52:55], v[200:203], v[164:167], v[52:55]
	v_mfma_f32_16x16x32_bf16 v[48:51], v[208:211], v[164:167], v[48:51]
	v_mfma_f32_16x16x32_bf16 v[36:39], v[200:203], v[176:179], v[36:39]
	v_mfma_f32_16x16x32_bf16 v[32:35], v[208:211], v[176:179], v[32:35]
	v_mfma_f32_16x16x32_bf16 v[20:23], v[200:203], v[184:187], v[20:23]
	v_mfma_f32_16x16x32_bf16 v[16:19], v[208:211], v[184:187], v[16:19]
	v_mfma_f32_16x16x32_bf16 v[4:7], v[200:203], v[192:195], v[4:7]
	v_mfma_f32_16x16x32_bf16 v[0:3], v[208:211], v[192:195], v[0:3]
	s_setprio 0
	s_add_i32 s28, 0, 0x18000
	v_add_u32_e32 v156, s28, v173
	s_barrier
	ds_read_b128 v[128:131], v156
	ds_read_b128 v[148:151], v156 offset:1024
	ds_read_b128 v[152:155], v156 offset:2048
	ds_read_b128 v[156:159], v156 offset:3072
	s_add_u32 s26, s26, s56
	s_addc_u32 s27, s27, 0
	s_mov_b32 m0, s86
	v_lshl_add_u64 v[196:197], s[26:27], 0, v[138:139]
	ds_read_b128 v[160:163], v175 offset:32768
	ds_read_b128 v[164:167], v175 offset:33792
	ds_read_b128 v[168:171], v175 offset:34816
	ds_read_b128 v[176:179], v175 offset:35840
	ds_read_b128 v[180:183], v175 offset:36864
	ds_read_b128 v[184:187], v175 offset:37888
	ds_read_b128 v[188:191], v175 offset:38912
	ds_read_b128 v[192:195], v175 offset:39936
	global_load_lds_dwordx4 v[196:197], off
	v_lshl_add_u64 v[196:197], s[26:27], 0, v[140:141]
	s_mov_b32 m0, s87
	s_nop 0
	global_load_lds_dwordx4 v[196:197], off
	s_waitcnt lgkmcnt(8)
	s_barrier
	s_waitcnt lgkmcnt(0)
	s_setprio 1
	s_waitcnt lgkmcnt(0)
	v_mfma_f32_16x16x32_bf16 v[124:127], v[128:131], v[160:163], v[124:127]
	v_mfma_f32_16x16x32_bf16 v[120:123], v[152:155], v[160:163], v[120:123]
	v_mfma_f32_16x16x32_bf16 v[108:111], v[128:131], v[168:171], v[108:111]
	v_mfma_f32_16x16x32_bf16 v[104:107], v[152:155], v[168:171], v[104:107]
	v_mfma_f32_16x16x32_bf16 v[92:95], v[128:131], v[180:183], v[92:95]
	v_mfma_f32_16x16x32_bf16 v[88:91], v[152:155], v[180:183], v[88:91]
	v_mfma_f32_16x16x32_bf16 v[76:79], v[128:131], v[188:191], v[76:79]
	v_mfma_f32_16x16x32_bf16 v[72:75], v[152:155], v[188:191], v[72:75]
	v_mfma_f32_16x16x32_bf16 v[124:127], v[148:151], v[164:167], v[124:127]
	v_mfma_f32_16x16x32_bf16 v[120:123], v[156:159], v[164:167], v[120:123]
	v_mfma_f32_16x16x32_bf16 v[108:111], v[148:151], v[176:179], v[108:111]
	v_mfma_f32_16x16x32_bf16 v[104:107], v[156:159], v[176:179], v[104:107]
	v_mfma_f32_16x16x32_bf16 v[92:95], v[148:151], v[184:187], v[92:95]
	v_mfma_f32_16x16x32_bf16 v[88:91], v[156:159], v[184:187], v[88:91]
	v_mfma_f32_16x16x32_bf16 v[76:79], v[148:151], v[192:195], v[76:79]
	v_mfma_f32_16x16x32_bf16 v[72:75], v[156:159], v[192:195], v[72:75]
	s_setprio 0
	s_barrier
	s_add_i32 s26, 0, 0x1c000
	s_add_i32 s27, s28, s97
	v_add_u32_e32 v208, s26, v173
	v_lshl_add_u64 v[212:213], v[212:213], 0, s[22:23]
	s_mov_b32 m0, s27
	ds_read_b128 v[196:199], v208
	ds_read_b128 v[200:203], v208 offset:1024
	ds_read_b128 v[204:207], v208 offset:2048
	ds_read_b128 v[208:211], v208 offset:3072
	global_load_lds_dwordx4 v[212:213], off
	v_lshl_add_u64 v[212:213], v[214:215], 0, s[22:23]
	s_add_i32 m0, s27, 0x2000
	s_nop 0
	global_load_lds_dwordx4 v[212:213], off
	s_barrier
	s_waitcnt lgkmcnt(0)
	s_setprio 1
	s_waitcnt lgkmcnt(0)
	v_mfma_f32_16x16x32_bf16 v[116:119], v[196:199], v[160:163], v[116:119]
	v_mfma_f32_16x16x32_bf16 v[112:115], v[204:207], v[160:163], v[112:115]
	v_mfma_f32_16x16x32_bf16 v[100:103], v[196:199], v[168:171], v[100:103]
	v_mfma_f32_16x16x32_bf16 v[96:99], v[204:207], v[168:171], v[96:99]
	v_mfma_f32_16x16x32_bf16 v[84:87], v[196:199], v[180:183], v[84:87]
	v_mfma_f32_16x16x32_bf16 v[80:83], v[204:207], v[180:183], v[80:83]
	v_mfma_f32_16x16x32_bf16 v[68:71], v[196:199], v[188:191], v[68:71]
	v_mfma_f32_16x16x32_bf16 v[64:67], v[204:207], v[188:191], v[64:67]
	v_mfma_f32_16x16x32_bf16 v[116:119], v[200:203], v[164:167], v[116:119]
	v_mfma_f32_16x16x32_bf16 v[112:115], v[208:211], v[164:167], v[112:115]
	v_mfma_f32_16x16x32_bf16 v[100:103], v[200:203], v[176:179], v[100:103]
	v_mfma_f32_16x16x32_bf16 v[96:99], v[208:211], v[176:179], v[96:99]
	v_mfma_f32_16x16x32_bf16 v[84:87], v[200:203], v[184:187], v[84:87]
	v_mfma_f32_16x16x32_bf16 v[80:83], v[208:211], v[184:187], v[80:83]
	v_mfma_f32_16x16x32_bf16 v[68:71], v[200:203], v[192:195], v[68:71]
	v_mfma_f32_16x16x32_bf16 v[64:67], v[208:211], v[192:195], v[64:67]
	s_setprio 0
	s_mov_b32 m0, s74
	v_lshl_add_u64 v[212:213], v[216:217], 0, s[22:23]
	s_barrier
; #define PG8_STAGE(bufoff, gbase, voff) do { _Pragma("unroll") for (int _i = 0; _i < 2; ++_i) \
;     __builtin_amdgcn_global_load_lds((const unsigned*)((const char*)(gbase) + (voff)[_i]), (LAS unsigned*)(lds + (bufoff) + ldsw + _i * 8192), 16, 0, 0); } while (0)
; #define PG8_LDA(dst, b, h) do { _Pragma("unroll") for (int m = 0; m < 4; ++m) _Pragma("unroll") for (int k = 0; k < 2; ++k) dst[m][k] = *(const LAS bf16x8*)(lds + PG8_SA(b, h) + aoff + m * 2048 + k * 1024); } while (0)
; #define PG8_MMA(ai, bj, At, Bt) do { __builtin_amdgcn_s_setprio(1); _Pragma("unroll") for (int m = 0; m < 4; ++m) _Pragma("unroll") for (int n = 0; n < 2; ++n) _Pragma("unroll") for (int k = 0; k < 2; ++k) \
;     acc[ai][bj][m][n] = __builtin_amdgcn_mfma_f32_16x16x32_bf16(Bt[n][k], At[m][k], acc[ai][bj][m][n], 0, 0, 0); __builtin_amdgcn_s_setprio(0); } while (0)
; #define PG8_WAIT_V(n) asm volatile("s_waitcnt vmcnt(" #n ")" ::: "memory")
; #define PG8_WAIT_L(n) asm volatile("s_waitcnt lgkmcnt(" #n ")" ::: "memory")
; #define PG8_BAR __builtin_amdgcn_s_barrier()
; #define PG8_SCHED __builtin_amdgcn_sched_barrier(0)
; template <class Epi>
; __device__ __forceinline__ void gemm_phase(LAS unsigned char* lds, const Gemm g, const Epi& E) {
;     ...
;       PG8_LDA(At, 1, 1); PG8_STAGE(PG8_SA(1, 0), a3, voffA);
;       PG8_BAR; PG8_WAIT_L(0); PG8_MMA(1, 0, At, B0); PG8_BAR; PG8_SCHED;
;       PG8_STAGE(PG8_SB(1, 1), b3 + hstepB, voffB);
;       PG8_WAIT_V(6); PG8_BAR; PG8_MMA(1, 1, At, B1); PG8_BAR;
;     }
;     {
; #pragma unroll
;       for (int ai = 0; ai < 2; ++ai)
; #pragma unroll
;         for (int m = 0; m < 4; ++m)
; #pragma unroll
;           for (int bj = 0; bj < 2; ++bj)
;           { E.st2(cur.w, cur.pm * BM + ai * HALF + wr * 64 + m * 16 + fr, cur.pn * BM + bj * HALF + wc * 32 + 8 * fq, acc[ai][bj][m][0], acc[ai][bj][m][1]); if (bj == 1 && (m & 1)) asm volatile("" ::: "memory"); }
	ds_read_b128 v[160:163], v175 offset:49152
	ds_read_b128 v[164:167], v175 offset:50176
	ds_read_b128 v[168:171], v175 offset:51200
	ds_read_b128 v[176:179], v175 offset:52224
	ds_read_b128 v[180:183], v175 offset:53248
	ds_read_b128 v[184:187], v175 offset:54272
	ds_read_b128 v[188:191], v175 offset:55296
	ds_read_b128 v[192:195], v175 offset:56320
	global_load_lds_dwordx4 v[212:213], off
	v_lshl_add_u64 v[212:213], v[218:219], 0, s[22:23]
	s_mov_b32 m0, s78
	s_nop 0
	global_load_lds_dwordx4 v[212:213], off
	s_barrier
	s_waitcnt lgkmcnt(0)
	s_setprio 1
	s_waitcnt lgkmcnt(0)
	v_mfma_f32_16x16x32_bf16 v[60:63], v[128:131], v[160:163], v[60:63]
	v_mfma_f32_16x16x32_bf16 v[56:59], v[152:155], v[160:163], v[56:59]
	v_mfma_f32_16x16x32_bf16 v[44:47], v[128:131], v[168:171], v[44:47]
	v_mfma_f32_16x16x32_bf16 v[40:43], v[152:155], v[168:171], v[40:43]
	v_mfma_f32_16x16x32_bf16 v[28:31], v[128:131], v[180:183], v[28:31]
	v_mfma_f32_16x16x32_bf16 v[24:27], v[152:155], v[180:183], v[24:27]
	v_mfma_f32_16x16x32_bf16 v[12:15], v[128:131], v[188:191], v[12:15]
	v_mfma_f32_16x16x32_bf16 v[8:11], v[152:155], v[188:191], v[8:11]
	v_mfma_f32_16x16x32_bf16 v[60:63], v[148:151], v[164:167], v[60:63]
	v_mfma_f32_16x16x32_bf16 v[56:59], v[156:159], v[164:167], v[56:59]
	v_mfma_f32_16x16x32_bf16 v[44:47], v[148:151], v[176:179], v[44:47]
	v_mfma_f32_16x16x32_bf16 v[40:43], v[156:159], v[176:179], v[40:43]
	v_mfma_f32_16x16x32_bf16 v[28:31], v[148:151], v[184:187], v[28:31]
	v_mfma_f32_16x16x32_bf16 v[24:27], v[156:159], v[184:187], v[24:27]
	v_mfma_f32_16x16x32_bf16 v[12:15], v[148:151], v[192:195], v[12:15]
	v_mfma_f32_16x16x32_bf16 v[8:11], v[156:159], v[192:195], v[8:11]
	s_setprio 0
	s_barrier
	s_add_i32 s26, s26, s97
	v_lshl_add_u64 v[128:129], v[220:221], 0, s[22:23]
	s_mov_b32 m0, s26
	s_nop 0
	global_load_lds_dwordx4 v[128:129], off
	v_lshl_add_u64 v[128:129], v[222:223], 0, s[22:23]
	s_add_i32 m0, s26, 0x2000
	s_nop 0
	global_load_lds_dwordx4 v[128:129], off
	s_waitcnt vmcnt(6)
	s_barrier
	s_setprio 1
	v_mfma_f32_16x16x32_bf16 v[52:55], v[196:199], v[160:163], v[52:55]
	v_mfma_f32_16x16x32_bf16 v[48:51], v[204:207], v[160:163], v[48:51]
	v_mfma_f32_16x16x32_bf16 v[36:39], v[196:199], v[168:171], v[36:39]
	v_mfma_f32_16x16x32_bf16 v[32:35], v[204:207], v[168:171], v[32:35]
	v_mfma_f32_16x16x32_bf16 v[20:23], v[196:199], v[180:183], v[20:23]
	v_mfma_f32_16x16x32_bf16 v[16:19], v[204:207], v[180:183], v[16:19]
	v_mfma_f32_16x16x32_bf16 v[4:7], v[196:199], v[188:191], v[4:7]
	v_mfma_f32_16x16x32_bf16 v[0:3], v[204:207], v[188:191], v[0:3]
	v_mfma_f32_16x16x32_bf16 v[52:55], v[200:203], v[164:167], v[52:55]
	v_mfma_f32_16x16x32_bf16 v[48:51], v[208:211], v[164:167], v[48:51]
	v_mfma_f32_16x16x32_bf16 v[36:39], v[200:203], v[176:179], v[36:39]
	v_mfma_f32_16x16x32_bf16 v[32:35], v[208:211], v[176:179], v[32:35]
	v_mfma_f32_16x16x32_bf16 v[20:23], v[200:203], v[184:187], v[20:23]
	v_mfma_f32_16x16x32_bf16 v[16:19], v[208:211], v[184:187], v[16:19]
	v_mfma_f32_16x16x32_bf16 v[4:7], v[200:203], v[192:195], v[4:7]
	v_mfma_f32_16x16x32_bf16 v[0:3], v[208:211], v[192:195], v[0:3]
	s_setprio 0
	s_add_u32 s2, s2, 0x100
	s_addc_u32 s3, s3, 0
	s_add_u32 s38, s38, 0x100
	s_addc_u32 s39, s39, 0
	s_cmp_ge_u32 s76, s72
	s_mov_b32 s26, s76
	s_barrier
	s_cbranch_scc0 .LBB0_579
	s_lshl_b32 s28, s53, 8
	v_lshl_add_u32 v150, s75, 8, v172
	s_cmp_eq_u32 s12, 0
	v_ashrrev_i32_e32 v151, 31, v150
	v_mad_i64_i32 v[164:165], s[2:3], v150, s54, 0
	v_mad_i64_i32 v[154:155], s[2:3], v150, s33, 0
	s_cselect_b32 s29, s40, s41
	v_lshlrev_b64 v[162:163], 10, v[150:151]
	v_cmp_gt_i32_e64 s[38:39], s92, v150
	v_lshlrev_b64 v[152:153], 12, v[150:151]
	v_or_b32_e32 v148, s28, v174
	s_cmp_eq_u32 s29, 3
	s_cbranch_scc1 .Lepi3
	s_cmp_eq_u32 s29, 4
	s_cbranch_scc1 .Lepi4
	s_cmp_eq_u32 s29, 6
	s_cbranch_scc1 .Lepi6
	s_cmp_lt_i32 s29, 4
	s_mov_b64 s[2:3], -1
	s_cbranch_scc1 .LBB0_593
	s_cmp_lt_i32 s29, 6
	s_cbranch_scc1 .LBB0_587
	s_cmp_gt_i32 s29, 6
	s_cbranch_scc0 .LBB0_584
	v_lshl_add_u64 v[128:129], s[58:59], 0, v[152:153]
	v_ashrrev_i32_e32 v149, 31, v148
	v_lshl_add_u64 v[160:161], v[148:149], 2, v[128:129]
	global_load_dwordx4 v[128:131], v[160:161], off nt
	global_load_dwordx4 v[156:159], v[160:161], off offset:16 nt
	s_mov_b64 s[2:3], 0
	s_waitcnt vmcnt(0)
	v_pk_add_f32 v[130:131], v[126:127], v[130:131]
	v_pk_add_f32 v[128:129], v[124:125], v[128:129]
	v_pk_add_f32 v[158:159], v[122:123], v[158:159]
	v_pk_add_f32 v[156:157], v[120:121], v[156:157]
	global_store_dwordx4 v[160:161], v[128:131], off nt
	global_store_dwordx4 v[160:161], v[156:159], off offset:16 nt

.Lepi6:
	v_mul_u32_u24_e32 v176, 0x1600, v150
	v_ashrrev_i32_e32 v177, 1, v148
	v_lshl_add_u32 v176, v177, 1, v176
	v_add_u32_e32 v177, 0x16000, v176
	v_add_u32_e32 v178, 0x2c000, v176
	v_add_u32_e32 v179, 0x42000, v176
	v_add_u32_e32 v180, 0xb0000, v176
	v_add_u32_e32 v181, 0xc6000, v176
	v_add_u32_e32 v182, 0xdc000, v176
	v_add_u32_e32 v183, 0xf2000, v176
	v_mul_f32_e32 v152, 0xbfb8aa3b, v124
	v_mul_f32_e32 v153, 0xbfb8aa3b, v125
	v_mul_f32_e32 v154, 0xbfb8aa3b, v126
	v_mul_f32_e32 v155, 0xbfb8aa3b, v127
	v_exp_f32_e32 v152, v152
	v_exp_f32_e32 v153, v153
	v_exp_f32_e32 v154, v154
	v_exp_f32_e32 v155, v155
	v_pk_add_f32 v[152:153], v[152:153], 1.0 op_sel_hi:[1,0]
	v_pk_add_f32 v[154:155], v[154:155], 1.0 op_sel_hi:[1,0]
	v_div_scale_f32 v156, s[38:39], v152, v152, 1.0
	v_div_scale_f32 v157, s[38:39], v153, v153, 1.0
	v_div_scale_f32 v158, s[38:39], v154, v154, 1.0
	v_div_scale_f32 v159, s[38:39], v155, v155, 1.0
	v_rcp_f32_e32 v160, v156
	v_rcp_f32_e32 v161, v157
	v_rcp_f32_e32 v162, v158
	v_rcp_f32_e32 v163, v159
	v_pk_fma_f32 v[164:165], v[156:157], v[160:161], 1.0 op_sel_hi:[1,1,0] neg_lo:[1,0,0] neg_hi:[1,0,0]
	v_pk_fma_f32 v[166:167], v[158:159], v[162:163], 1.0 op_sel_hi:[1,1,0] neg_lo:[1,0,0] neg_hi:[1,0,0]
	v_pk_fma_f32 v[160:161], v[164:165], v[160:161], v[160:161]
	v_pk_fma_f32 v[162:163], v[166:167], v[162:163], v[162:163]
	v_div_scale_f32 v168, s[2:3], 1.0, v152, 1.0
	v_div_scale_f32 v169, s[26:27], 1.0, v153, 1.0
	v_div_scale_f32 v170, s[28:29], 1.0, v154, 1.0
	v_div_scale_f32 v171, vcc, 1.0, v155, 1.0
	v_pk_mul_f32 v[128:129], v[168:169], v[160:161]
	v_pk_mul_f32 v[130:131], v[170:171], v[162:163]
	v_pk_fma_f32 v[164:165], v[156:157], v[128:129], v[168:169] neg_lo:[1,0,0] neg_hi:[1,0,0]
	v_pk_fma_f32 v[166:167], v[158:159], v[130:131], v[170:171] neg_lo:[1,0,0] neg_hi:[1,0,0]
	v_pk_fma_f32 v[128:129], v[164:165], v[160:161], v[128:129]
	v_pk_fma_f32 v[130:131], v[166:167], v[162:163], v[130:131]
	v_pk_fma_f32 v[156:157], v[156:157], v[128:129], v[168:169] neg_lo:[1,0,0] neg_hi:[1,0,0]
	v_pk_fma_f32 v[158:159], v[158:159], v[130:131], v[170:171] neg_lo:[1,0,0] neg_hi:[1,0,0]
	v_div_fmas_f32 v159, v159, v163, v131
	s_mov_b64 vcc, s[28:29]
	v_div_fmas_f32 v158, v158, v162, v130
	s_mov_b64 vcc, s[26:27]
	v_div_fmas_f32 v157, v157, v161, v129
	s_mov_b64 vcc, s[2:3]
	v_div_fmas_f32 v156, v156, v160, v128
	v_div_fixup_f32 v152, v156, v152, 1.0
	v_div_fixup_f32 v153, v157, v153, 1.0
	v_div_fixup_f32 v154, v158, v154, 1.0
	v_div_fixup_f32 v155, v159, v155, 1.0
	v_pk_mul_f32 v[152:153], v[124:125], v[152:153]
	v_pk_mul_f32 v[154:155], v[126:127], v[154:155]
	v_pk_mul_f32 v[152:153], v[120:121], v[152:153]
	v_pk_mul_f32 v[154:155], v[122:123], v[154:155]
	v_cvt_pk_bf16_f32 v184, v152, v153
	v_cvt_pk_bf16_f32 v185, v154, v155
	global_store_dwordx2 v176, v[184:185], s[64:65]
	v_mul_f32_e32 v152, 0xbfb8aa3b, v116
	v_mul_f32_e32 v153, 0xbfb8aa3b, v117
	v_mul_f32_e32 v154, 0xbfb8aa3b, v118
	v_mul_f32_e32 v155, 0xbfb8aa3b, v119
	v_exp_f32_e32 v152, v152
	v_exp_f32_e32 v153, v153
	v_exp_f32_e32 v154, v154
	v_exp_f32_e32 v155, v155
	v_pk_add_f32 v[152:153], v[152:153], 1.0 op_sel_hi:[1,0]
	v_pk_add_f32 v[154:155], v[154:155], 1.0 op_sel_hi:[1,0]
	v_div_scale_f32 v156, s[38:39], v152, v152, 1.0
	v_div_scale_f32 v157, s[38:39], v153, v153, 1.0
	v_div_scale_f32 v158, s[38:39], v154, v154, 1.0
	v_div_scale_f32 v159, s[38:39], v155, v155, 1.0
	v_rcp_f32_e32 v160, v156
	v_rcp_f32_e32 v161, v157
	v_rcp_f32_e32 v162, v158
	v_rcp_f32_e32 v163, v159
	v_pk_fma_f32 v[164:165], v[156:157], v[160:161], 1.0 op_sel_hi:[1,1,0] neg_lo:[1,0,0] neg_hi:[1,0,0]
	v_pk_fma_f32 v[166:167], v[158:159], v[162:163], 1.0 op_sel_hi:[1,1,0] neg_lo:[1,0,0] neg_hi:[1,0,0]
	v_pk_fma_f32 v[160:161], v[164:165], v[160:161], v[160:161]
	v_pk_fma_f32 v[162:163], v[166:167], v[162:163], v[162:163]
	v_div_scale_f32 v168, s[2:3], 1.0, v152, 1.0
	v_div_scale_f32 v169, s[26:27], 1.0, v153, 1.0
	v_div_scale_f32 v170, s[28:29], 1.0, v154, 1.0
	v_div_scale_f32 v171, vcc, 1.0, v155, 1.0
	v_pk_mul_f32 v[128:129], v[168:169], v[160:161]
	v_pk_mul_f32 v[130:131], v[170:171], v[162:163]
	v_pk_fma_f32 v[164:165], v[156:157], v[128:129], v[168:169] neg_lo:[1,0,0] neg_hi:[1,0,0]
	v_pk_fma_f32 v[166:167], v[158:159], v[130:131], v[170:171] neg_lo:[1,0,0] neg_hi:[1,0,0]
	v_pk_fma_f32 v[128:129], v[164:165], v[160:161], v[128:129]
	v_pk_fma_f32 v[130:131], v[166:167], v[162:163], v[130:131]
	v_pk_fma_f32 v[156:157], v[156:157], v[128:129], v[168:169] neg_lo:[1,0,0] neg_hi:[1,0,0]
	v_pk_fma_f32 v[158:159], v[158:159], v[130:131], v[170:171] neg_lo:[1,0,0] neg_hi:[1,0,0]
	v_div_fmas_f32 v159, v159, v163, v131
	s_mov_b64 vcc, s[28:29]
	v_div_fmas_f32 v158, v158, v162, v130
	s_mov_b64 vcc, s[26:27]
	v_div_fmas_f32 v157, v157, v161, v129
	s_mov_b64 vcc, s[2:3]
	v_div_fmas_f32 v156, v156, v160, v128
	v_div_fixup_f32 v152, v156, v152, 1.0
	v_div_fixup_f32 v153, v157, v153, 1.0
	v_div_fixup_f32 v154, v158, v154, 1.0
	v_div_fixup_f32 v155, v159, v155, 1.0
	v_pk_mul_f32 v[152:153], v[116:117], v[152:153]
	v_pk_mul_f32 v[154:155], v[118:119], v[154:155]
	v_pk_mul_f32 v[152:153], v[112:113], v[152:153]
	v_pk_mul_f32 v[154:155], v[114:115], v[154:155]
	v_cvt_pk_bf16_f32 v186, v152, v153
	v_cvt_pk_bf16_f32 v187, v154, v155
	global_store_dwordx2 v176, v[186:187], s[64:65] offset:128
	v_mul_f32_e32 v152, 0xbfb8aa3b, v108
	v_mul_f32_e32 v153, 0xbfb8aa3b, v109
	v_mul_f32_e32 v154, 0xbfb8aa3b, v110
	v_mul_f32_e32 v155, 0xbfb8aa3b, v111
	v_exp_f32_e32 v152, v152
	v_exp_f32_e32 v153, v153
	v_exp_f32_e32 v154, v154
	v_exp_f32_e32 v155, v155
	v_pk_add_f32 v[152:153], v[152:153], 1.0 op_sel_hi:[1,0]
	v_pk_add_f32 v[154:155], v[154:155], 1.0 op_sel_hi:[1,0]
	v_div_scale_f32 v156, s[38:39], v152, v152, 1.0
	v_div_scale_f32 v157, s[38:39], v153, v153, 1.0
	v_div_scale_f32 v158, s[38:39], v154, v154, 1.0
	v_div_scale_f32 v159, s[38:39], v155, v155, 1.0
	v_rcp_f32_e32 v160, v156
	v_rcp_f32_e32 v161, v157
	v_rcp_f32_e32 v162, v158
	v_rcp_f32_e32 v163, v159
	v_pk_fma_f32 v[164:165], v[156:157], v[160:161], 1.0 op_sel_hi:[1,1,0] neg_lo:[1,0,0] neg_hi:[1,0,0]
	v_pk_fma_f32 v[166:167], v[158:159], v[162:163], 1.0 op_sel_hi:[1,1,0] neg_lo:[1,0,0] neg_hi:[1,0,0]
	v_pk_fma_f32 v[160:161], v[164:165], v[160:161], v[160:161]
	v_pk_fma_f32 v[162:163], v[166:167], v[162:163], v[162:163]
	v_div_scale_f32 v168, s[2:3], 1.0, v152, 1.0
	v_div_scale_f32 v169, s[26:27], 1.0, v153, 1.0
	v_div_scale_f32 v170, s[28:29], 1.0, v154, 1.0
	v_div_scale_f32 v171, vcc, 1.0, v155, 1.0
	v_pk_mul_f32 v[128:129], v[168:169], v[160:161]
	v_pk_mul_f32 v[130:131], v[170:171], v[162:163]
	v_pk_fma_f32 v[164:165], v[156:157], v[128:129], v[168:169] neg_lo:[1,0,0] neg_hi:[1,0,0]
	v_pk_fma_f32 v[166:167], v[158:159], v[130:131], v[170:171] neg_lo:[1,0,0] neg_hi:[1,0,0]
	v_pk_fma_f32 v[128:129], v[164:165], v[160:161], v[128:129]
	v_pk_fma_f32 v[130:131], v[166:167], v[162:163], v[130:131]
	v_pk_fma_f32 v[156:157], v[156:157], v[128:129], v[168:169] neg_lo:[1,0,0] neg_hi:[1,0,0]
	v_pk_fma_f32 v[158:159], v[158:159], v[130:131], v[170:171] neg_lo:[1,0,0] neg_hi:[1,0,0]
	v_div_fmas_f32 v159, v159, v163, v131
	s_mov_b64 vcc, s[28:29]
	v_div_fmas_f32 v158, v158, v162, v130
	s_mov_b64 vcc, s[26:27]
	v_div_fmas_f32 v157, v157, v161, v129
	s_mov_b64 vcc, s[2:3]
	v_div_fmas_f32 v156, v156, v160, v128
	v_div_fixup_f32 v152, v156, v152, 1.0
	v_div_fixup_f32 v153, v157, v153, 1.0
	v_div_fixup_f32 v154, v158, v154, 1.0
	v_div_fixup_f32 v155, v159, v155, 1.0
	v_pk_mul_f32 v[152:153], v[108:109], v[152:153]
	v_pk_mul_f32 v[154:155], v[110:111], v[154:155]
	v_pk_mul_f32 v[152:153], v[104:105], v[152:153]
	v_pk_mul_f32 v[154:155], v[106:107], v[154:155]
	v_cvt_pk_bf16_f32 v184, v152, v153
	v_cvt_pk_bf16_f32 v185, v154, v155
	global_store_dwordx2 v177, v[184:185], s[64:65]
	v_mul_f32_e32 v152, 0xbfb8aa3b, v100
	v_mul_f32_e32 v153, 0xbfb8aa3b, v101
	v_mul_f32_e32 v154, 0xbfb8aa3b, v102
	v_mul_f32_e32 v155, 0xbfb8aa3b, v103
	v_exp_f32_e32 v152, v152
	v_exp_f32_e32 v153, v153
	v_exp_f32_e32 v154, v154
	v_exp_f32_e32 v155, v155
	v_pk_add_f32 v[152:153], v[152:153], 1.0 op_sel_hi:[1,0]
	v_pk_add_f32 v[154:155], v[154:155], 1.0 op_sel_hi:[1,0]
	v_div_scale_f32 v156, s[38:39], v152, v152, 1.0
	v_div_scale_f32 v157, s[38:39], v153, v153, 1.0
	v_div_scale_f32 v158, s[38:39], v154, v154, 1.0
	v_div_scale_f32 v159, s[38:39], v155, v155, 1.0
	v_rcp_f32_e32 v160, v156
	v_rcp_f32_e32 v161, v157
	v_rcp_f32_e32 v162, v158
	v_rcp_f32_e32 v163, v159
	v_pk_fma_f32 v[164:165], v[156:157], v[160:161], 1.0 op_sel_hi:[1,1,0] neg_lo:[1,0,0] neg_hi:[1,0,0]
	v_pk_fma_f32 v[166:167], v[158:159], v[162:163], 1.0 op_sel_hi:[1,1,0] neg_lo:[1,0,0] neg_hi:[1,0,0]
	v_pk_fma_f32 v[160:161], v[164:165], v[160:161], v[160:161]
	v_pk_fma_f32 v[162:163], v[166:167], v[162:163], v[162:163]
	v_div_scale_f32 v168, s[2:3], 1.0, v152, 1.0
	v_div_scale_f32 v169, s[26:27], 1.0, v153, 1.0
	v_div_scale_f32 v170, s[28:29], 1.0, v154, 1.0
	v_div_scale_f32 v171, vcc, 1.0, v155, 1.0
	v_pk_mul_f32 v[128:129], v[168:169], v[160:161]
	v_pk_mul_f32 v[130:131], v[170:171], v[162:163]
	v_pk_fma_f32 v[164:165], v[156:157], v[128:129], v[168:169] neg_lo:[1,0,0] neg_hi:[1,0,0]
	v_pk_fma_f32 v[166:167], v[158:159], v[130:131], v[170:171] neg_lo:[1,0,0] neg_hi:[1,0,0]
	v_pk_fma_f32 v[128:129], v[164:165], v[160:161], v[128:129]
	v_pk_fma_f32 v[130:131], v[166:167], v[162:163], v[130:131]
	v_pk_fma_f32 v[156:157], v[156:157], v[128:129], v[168:169] neg_lo:[1,0,0] neg_hi:[1,0,0]
	v_pk_fma_f32 v[158:159], v[158:159], v[130:131], v[170:171] neg_lo:[1,0,0] neg_hi:[1,0,0]
	v_div_fmas_f32 v159, v159, v163, v131
	s_mov_b64 vcc, s[28:29]
	v_div_fmas_f32 v158, v158, v162, v130
	s_mov_b64 vcc, s[26:27]
	v_div_fmas_f32 v157, v157, v161, v129
	s_mov_b64 vcc, s[2:3]
	v_div_fmas_f32 v156, v156, v160, v128
	v_div_fixup_f32 v152, v156, v152, 1.0
	v_div_fixup_f32 v153, v157, v153, 1.0
	v_div_fixup_f32 v154, v158, v154, 1.0
	v_div_fixup_f32 v155, v159, v155, 1.0
	v_pk_mul_f32 v[152:153], v[100:101], v[152:153]
	v_pk_mul_f32 v[154:155], v[102:103], v[154:155]
	v_pk_mul_f32 v[152:153], v[96:97], v[152:153]
	v_pk_mul_f32 v[154:155], v[98:99], v[154:155]
	v_cvt_pk_bf16_f32 v186, v152, v153
	v_cvt_pk_bf16_f32 v187, v154, v155
	global_store_dwordx2 v177, v[186:187], s[64:65] offset:128
	v_mul_f32_e32 v152, 0xbfb8aa3b, v92
	v_mul_f32_e32 v153, 0xbfb8aa3b, v93
	v_mul_f32_e32 v154, 0xbfb8aa3b, v94
	v_mul_f32_e32 v155, 0xbfb8aa3b, v95
	v_exp_f32_e32 v152, v152
	v_exp_f32_e32 v153, v153
	v_exp_f32_e32 v154, v154
	v_exp_f32_e32 v155, v155
	v_pk_add_f32 v[152:153], v[152:153], 1.0 op_sel_hi:[1,0]
	v_pk_add_f32 v[154:155], v[154:155], 1.0 op_sel_hi:[1,0]
	v_div_scale_f32 v156, s[38:39], v152, v152, 1.0
	v_div_scale_f32 v157, s[38:39], v153, v153, 1.0
	v_div_scale_f32 v158, s[38:39], v154, v154, 1.0
	v_div_scale_f32 v159, s[38:39], v155, v155, 1.0
	v_rcp_f32_e32 v160, v156
	v_rcp_f32_e32 v161, v157
	v_rcp_f32_e32 v162, v158
	v_rcp_f32_e32 v163, v159
	v_pk_fma_f32 v[164:165], v[156:157], v[160:161], 1.0 op_sel_hi:[1,1,0] neg_lo:[1,0,0] neg_hi:[1,0,0]
	v_pk_fma_f32 v[166:167], v[158:159], v[162:163], 1.0 op_sel_hi:[1,1,0] neg_lo:[1,0,0] neg_hi:[1,0,0]
	v_pk_fma_f32 v[160:161], v[164:165], v[160:161], v[160:161]
	v_pk_fma_f32 v[162:163], v[166:167], v[162:163], v[162:163]
	v_div_scale_f32 v168, s[2:3], 1.0, v152, 1.0
	v_div_scale_f32 v169, s[26:27], 1.0, v153, 1.0
	v_div_scale_f32 v170, s[28:29], 1.0, v154, 1.0
	v_div_scale_f32 v171, vcc, 1.0, v155, 1.0
	v_pk_mul_f32 v[128:129], v[168:169], v[160:161]
	v_pk_mul_f32 v[130:131], v[170:171], v[162:163]
	v_pk_fma_f32 v[164:165], v[156:157], v[128:129], v[168:169] neg_lo:[1,0,0] neg_hi:[1,0,0]
	v_pk_fma_f32 v[166:167], v[158:159], v[130:131], v[170:171] neg_lo:[1,0,0] neg_hi:[1,0,0]
	v_pk_fma_f32 v[128:129], v[164:165], v[160:161], v[128:129]
	v_pk_fma_f32 v[130:131], v[166:167], v[162:163], v[130:131]
	v_pk_fma_f32 v[156:157], v[156:157], v[128:129], v[168:169] neg_lo:[1,0,0] neg_hi:[1,0,0]
	v_pk_fma_f32 v[158:159], v[158:159], v[130:131], v[170:171] neg_lo:[1,0,0] neg_hi:[1,0,0]
	v_div_fmas_f32 v159, v159, v163, v131
	s_mov_b64 vcc, s[28:29]
	v_div_fmas_f32 v158, v158, v162, v130
	s_mov_b64 vcc, s[26:27]
	v_div_fmas_f32 v157, v157, v161, v129
	s_mov_b64 vcc, s[2:3]
	v_div_fmas_f32 v156, v156, v160, v128
	v_div_fixup_f32 v152, v156, v152, 1.0
	v_div_fixup_f32 v153, v157, v153, 1.0
	v_div_fixup_f32 v154, v158, v154, 1.0
	v_div_fixup_f32 v155, v159, v155, 1.0
	v_pk_mul_f32 v[152:153], v[92:93], v[152:153]
	v_pk_mul_f32 v[154:155], v[94:95], v[154:155]
	v_pk_mul_f32 v[152:153], v[88:89], v[152:153]
	v_pk_mul_f32 v[154:155], v[90:91], v[154:155]
	v_cvt_pk_bf16_f32 v184, v152, v153
	v_cvt_pk_bf16_f32 v185, v154, v155
	global_store_dwordx2 v178, v[184:185], s[64:65]
	v_mul_f32_e32 v152, 0xbfb8aa3b, v84
	v_mul_f32_e32 v153, 0xbfb8aa3b, v85
	v_mul_f32_e32 v154, 0xbfb8aa3b, v86
	v_mul_f32_e32 v155, 0xbfb8aa3b, v87
	v_exp_f32_e32 v152, v152
	v_exp_f32_e32 v153, v153
	v_exp_f32_e32 v154, v154
	v_exp_f32_e32 v155, v155
	v_pk_add_f32 v[152:153], v[152:153], 1.0 op_sel_hi:[1,0]
	v_pk_add_f32 v[154:155], v[154:155], 1.0 op_sel_hi:[1,0]
	v_div_scale_f32 v156, s[38:39], v152, v152, 1.0
	v_div_scale_f32 v157, s[38:39], v153, v153, 1.0
	v_div_scale_f32 v158, s[38:39], v154, v154, 1.0
	v_div_scale_f32 v159, s[38:39], v155, v155, 1.0
	v_rcp_f32_e32 v160, v156
	v_rcp_f32_e32 v161, v157
	v_rcp_f32_e32 v162, v158
	v_rcp_f32_e32 v163, v159
	v_pk_fma_f32 v[164:165], v[156:157], v[160:161], 1.0 op_sel_hi:[1,1,0] neg_lo:[1,0,0] neg_hi:[1,0,0]
	v_pk_fma_f32 v[166:167], v[158:159], v[162:163], 1.0 op_sel_hi:[1,1,0] neg_lo:[1,0,0] neg_hi:[1,0,0]
	v_pk_fma_f32 v[160:161], v[164:165], v[160:161], v[160:161]
	v_pk_fma_f32 v[162:163], v[166:167], v[162:163], v[162:163]
	v_div_scale_f32 v168, s[2:3], 1.0, v152, 1.0
	v_div_scale_f32 v169, s[26:27], 1.0, v153, 1.0
	v_div_scale_f32 v170, s[28:29], 1.0, v154, 1.0
	v_div_scale_f32 v171, vcc, 1.0, v155, 1.0
	v_pk_mul_f32 v[128:129], v[168:169], v[160:161]
	v_pk_mul_f32 v[130:131], v[170:171], v[162:163]
	v_pk_fma_f32 v[164:165], v[156:157], v[128:129], v[168:169] neg_lo:[1,0,0] neg_hi:[1,0,0]
	v_pk_fma_f32 v[166:167], v[158:159], v[130:131], v[170:171] neg_lo:[1,0,0] neg_hi:[1,0,0]
	v_pk_fma_f32 v[128:129], v[164:165], v[160:161], v[128:129]
	v_pk_fma_f32 v[130:131], v[166:167], v[162:163], v[130:131]
	v_pk_fma_f32 v[156:157], v[156:157], v[128:129], v[168:169] neg_lo:[1,0,0] neg_hi:[1,0,0]
	v_pk_fma_f32 v[158:159], v[158:159], v[130:131], v[170:171] neg_lo:[1,0,0] neg_hi:[1,0,0]
	v_div_fmas_f32 v159, v159, v163, v131
	s_mov_b64 vcc, s[28:29]
	v_div_fmas_f32 v158, v158, v162, v130
	s_mov_b64 vcc, s[26:27]
	v_div_fmas_f32 v157, v157, v161, v129
	s_mov_b64 vcc, s[2:3]
	v_div_fmas_f32 v156, v156, v160, v128
	v_div_fixup_f32 v152, v156, v152, 1.0
	v_div_fixup_f32 v153, v157, v153, 1.0
	v_div_fixup_f32 v154, v158, v154, 1.0
	v_div_fixup_f32 v155, v159, v155, 1.0
	v_pk_mul_f32 v[152:153], v[84:85], v[152:153]
	v_pk_mul_f32 v[154:155], v[86:87], v[154:155]
	v_pk_mul_f32 v[152:153], v[80:81], v[152:153]
	v_pk_mul_f32 v[154:155], v[82:83], v[154:155]
	v_cvt_pk_bf16_f32 v186, v152, v153
	v_cvt_pk_bf16_f32 v187, v154, v155
	global_store_dwordx2 v178, v[186:187], s[64:65] offset:128
	v_mul_f32_e32 v152, 0xbfb8aa3b, v76
	v_mul_f32_e32 v153, 0xbfb8aa3b, v77
	v_mul_f32_e32 v154, 0xbfb8aa3b, v78
	v_mul_f32_e32 v155, 0xbfb8aa3b, v79
	v_exp_f32_e32 v152, v152
	v_exp_f32_e32 v153, v153
	v_exp_f32_e32 v154, v154
	v_exp_f32_e32 v155, v155
	v_pk_add_f32 v[152:153], v[152:153], 1.0 op_sel_hi:[1,0]
	v_pk_add_f32 v[154:155], v[154:155], 1.0 op_sel_hi:[1,0]
	v_div_scale_f32 v156, s[38:39], v152, v152, 1.0
	v_div_scale_f32 v157, s[38:39], v153, v153, 1.0
	v_div_scale_f32 v158, s[38:39], v154, v154, 1.0
	v_div_scale_f32 v159, s[38:39], v155, v155, 1.0
	v_rcp_f32_e32 v160, v156
	v_rcp_f32_e32 v161, v157
	v_rcp_f32_e32 v162, v158
	v_rcp_f32_e32 v163, v159
	v_pk_fma_f32 v[164:165], v[156:157], v[160:161], 1.0 op_sel_hi:[1,1,0] neg_lo:[1,0,0] neg_hi:[1,0,0]
	v_pk_fma_f32 v[166:167], v[158:159], v[162:163], 1.0 op_sel_hi:[1,1,0] neg_lo:[1,0,0] neg_hi:[1,0,0]
	v_pk_fma_f32 v[160:161], v[164:165], v[160:161], v[160:161]
	v_pk_fma_f32 v[162:163], v[166:167], v[162:163], v[162:163]
	v_div_scale_f32 v168, s[2:3], 1.0, v152, 1.0
	v_div_scale_f32 v169, s[26:27], 1.0, v153, 1.0
	v_div_scale_f32 v170, s[28:29], 1.0, v154, 1.0
	v_div_scale_f32 v171, vcc, 1.0, v155, 1.0
	v_pk_mul_f32 v[128:129], v[168:169], v[160:161]
	v_pk_mul_f32 v[130:131], v[170:171], v[162:163]
	v_pk_fma_f32 v[164:165], v[156:157], v[128:129], v[168:169] neg_lo:[1,0,0] neg_hi:[1,0,0]
	v_pk_fma_f32 v[166:167], v[158:159], v[130:131], v[170:171] neg_lo:[1,0,0] neg_hi:[1,0,0]
	v_pk_fma_f32 v[128:129], v[164:165], v[160:161], v[128:129]
	v_pk_fma_f32 v[130:131], v[166:167], v[162:163], v[130:131]
	v_pk_fma_f32 v[156:157], v[156:157], v[128:129], v[168:169] neg_lo:[1,0,0] neg_hi:[1,0,0]
	v_pk_fma_f32 v[158:159], v[158:159], v[130:131], v[170:171] neg_lo:[1,0,0] neg_hi:[1,0,0]
	v_div_fmas_f32 v159, v159, v163, v131
	s_mov_b64 vcc, s[28:29]
	v_div_fmas_f32 v158, v158, v162, v130
	s_mov_b64 vcc, s[26:27]
	v_div_fmas_f32 v157, v157, v161, v129
	s_mov_b64 vcc, s[2:3]
	v_div_fmas_f32 v156, v156, v160, v128
	v_div_fixup_f32 v152, v156, v152, 1.0
	v_div_fixup_f32 v153, v157, v153, 1.0
	v_div_fixup_f32 v154, v158, v154, 1.0
	v_div_fixup_f32 v155, v159, v155, 1.0
	v_pk_mul_f32 v[152:153], v[76:77], v[152:153]
	v_pk_mul_f32 v[154:155], v[78:79], v[154:155]
	v_pk_mul_f32 v[152:153], v[72:73], v[152:153]
	v_pk_mul_f32 v[154:155], v[74:75], v[154:155]
	v_cvt_pk_bf16_f32 v184, v152, v153
	v_cvt_pk_bf16_f32 v185, v154, v155
	global_store_dwordx2 v179, v[184:185], s[64:65]
	v_mul_f32_e32 v152, 0xbfb8aa3b, v68
	v_mul_f32_e32 v153, 0xbfb8aa3b, v69
	v_mul_f32_e32 v154, 0xbfb8aa3b, v70
	v_mul_f32_e32 v155, 0xbfb8aa3b, v71
	v_exp_f32_e32 v152, v152
	v_exp_f32_e32 v153, v153
	v_exp_f32_e32 v154, v154
	v_exp_f32_e32 v155, v155
	v_pk_add_f32 v[152:153], v[152:153], 1.0 op_sel_hi:[1,0]
	v_pk_add_f32 v[154:155], v[154:155], 1.0 op_sel_hi:[1,0]
	v_div_scale_f32 v156, s[38:39], v152, v152, 1.0
	v_div_scale_f32 v157, s[38:39], v153, v153, 1.0
	v_div_scale_f32 v158, s[38:39], v154, v154, 1.0
	v_div_scale_f32 v159, s[38:39], v155, v155, 1.0
	v_rcp_f32_e32 v160, v156
	v_rcp_f32_e32 v161, v157
	v_rcp_f32_e32 v162, v158
	v_rcp_f32_e32 v163, v159
	v_pk_fma_f32 v[164:165], v[156:157], v[160:161], 1.0 op_sel_hi:[1,1,0] neg_lo:[1,0,0] neg_hi:[1,0,0]
	v_pk_fma_f32 v[166:167], v[158:159], v[162:163], 1.0 op_sel_hi:[1,1,0] neg_lo:[1,0,0] neg_hi:[1,0,0]
	v_pk_fma_f32 v[160:161], v[164:165], v[160:161], v[160:161]
	v_pk_fma_f32 v[162:163], v[166:167], v[162:163], v[162:163]
	v_div_scale_f32 v168, s[2:3], 1.0, v152, 1.0
	v_div_scale_f32 v169, s[26:27], 1.0, v153, 1.0
	v_div_scale_f32 v170, s[28:29], 1.0, v154, 1.0
	v_div_scale_f32 v171, vcc, 1.0, v155, 1.0
	v_pk_mul_f32 v[128:129], v[168:169], v[160:161]
	v_pk_mul_f32 v[130:131], v[170:171], v[162:163]
	v_pk_fma_f32 v[164:165], v[156:157], v[128:129], v[168:169] neg_lo:[1,0,0] neg_hi:[1,0,0]
	v_pk_fma_f32 v[166:167], v[158:159], v[130:131], v[170:171] neg_lo:[1,0,0] neg_hi:[1,0,0]
	v_pk_fma_f32 v[128:129], v[164:165], v[160:161], v[128:129]
	v_pk_fma_f32 v[130:131], v[166:167], v[162:163], v[130:131]
	v_pk_fma_f32 v[156:157], v[156:157], v[128:129], v[168:169] neg_lo:[1,0,0] neg_hi:[1,0,0]
	v_pk_fma_f32 v[158:159], v[158:159], v[130:131], v[170:171] neg_lo:[1,0,0] neg_hi:[1,0,0]
	v_div_fmas_f32 v159, v159, v163, v131
	s_mov_b64 vcc, s[28:29]
	v_div_fmas_f32 v158, v158, v162, v130
	s_mov_b64 vcc, s[26:27]
	v_div_fmas_f32 v157, v157, v161, v129
	s_mov_b64 vcc, s[2:3]
	v_div_fmas_f32 v156, v156, v160, v128
	v_div_fixup_f32 v152, v156, v152, 1.0
	v_div_fixup_f32 v153, v157, v153, 1.0
	v_div_fixup_f32 v154, v158, v154, 1.0
	v_div_fixup_f32 v155, v159, v155, 1.0
	v_pk_mul_f32 v[152:153], v[68:69], v[152:153]
	v_pk_mul_f32 v[154:155], v[70:71], v[154:155]
	v_pk_mul_f32 v[152:153], v[64:65], v[152:153]
	v_pk_mul_f32 v[154:155], v[66:67], v[154:155]
	v_cvt_pk_bf16_f32 v186, v152, v153
	v_cvt_pk_bf16_f32 v187, v154, v155
	global_store_dwordx2 v179, v[186:187], s[64:65] offset:128
	v_mul_f32_e32 v152, 0xbfb8aa3b, v60
	v_mul_f32_e32 v153, 0xbfb8aa3b, v61
	v_mul_f32_e32 v154, 0xbfb8aa3b, v62
	v_mul_f32_e32 v155, 0xbfb8aa3b, v63
	v_exp_f32_e32 v152, v152
	v_exp_f32_e32 v153, v153
	v_exp_f32_e32 v154, v154
	v_exp_f32_e32 v155, v155
	v_pk_add_f32 v[152:153], v[152:153], 1.0 op_sel_hi:[1,0]
	v_pk_add_f32 v[154:155], v[154:155], 1.0 op_sel_hi:[1,0]
	v_div_scale_f32 v156, s[38:39], v152, v152, 1.0
	v_div_scale_f32 v157, s[38:39], v153, v153, 1.0
	v_div_scale_f32 v158, s[38:39], v154, v154, 1.0
	v_div_scale_f32 v159, s[38:39], v155, v155, 1.0
	v_rcp_f32_e32 v160, v156
	v_rcp_f32_e32 v161, v157
	v_rcp_f32_e32 v162, v158
	v_rcp_f32_e32 v163, v159
	v_pk_fma_f32 v[164:165], v[156:157], v[160:161], 1.0 op_sel_hi:[1,1,0] neg_lo:[1,0,0] neg_hi:[1,0,0]
	v_pk_fma_f32 v[166:167], v[158:159], v[162:163], 1.0 op_sel_hi:[1,1,0] neg_lo:[1,0,0] neg_hi:[1,0,0]
	v_pk_fma_f32 v[160:161], v[164:165], v[160:161], v[160:161]
	v_pk_fma_f32 v[162:163], v[166:167], v[162:163], v[162:163]
	v_div_scale_f32 v168, s[2:3], 1.0, v152, 1.0
	v_div_scale_f32 v169, s[26:27], 1.0, v153, 1.0
	v_div_scale_f32 v170, s[28:29], 1.0, v154, 1.0
	v_div_scale_f32 v171, vcc, 1.0, v155, 1.0
	v_pk_mul_f32 v[128:129], v[168:169], v[160:161]
	v_pk_mul_f32 v[130:131], v[170:171], v[162:163]
	v_pk_fma_f32 v[164:165], v[156:157], v[128:129], v[168:169] neg_lo:[1,0,0] neg_hi:[1,0,0]
	v_pk_fma_f32 v[166:167], v[158:159], v[130:131], v[170:171] neg_lo:[1,0,0] neg_hi:[1,0,0]
	v_pk_fma_f32 v[128:129], v[164:165], v[160:161], v[128:129]
	v_pk_fma_f32 v[130:131], v[166:167], v[162:163], v[130:131]
	v_pk_fma_f32 v[156:157], v[156:157], v[128:129], v[168:169] neg_lo:[1,0,0] neg_hi:[1,0,0]
	v_pk_fma_f32 v[158:159], v[158:159], v[130:131], v[170:171] neg_lo:[1,0,0] neg_hi:[1,0,0]
	v_div_fmas_f32 v159, v159, v163, v131
	s_mov_b64 vcc, s[28:29]
	v_div_fmas_f32 v158, v158, v162, v130
	s_mov_b64 vcc, s[26:27]
	v_div_fmas_f32 v157, v157, v161, v129
	s_mov_b64 vcc, s[2:3]
	v_div_fmas_f32 v156, v156, v160, v128
	v_div_fixup_f32 v152, v156, v152, 1.0
	v_div_fixup_f32 v153, v157, v153, 1.0
	v_div_fixup_f32 v154, v158, v154, 1.0
	v_div_fixup_f32 v155, v159, v155, 1.0
	v_pk_mul_f32 v[152:153], v[60:61], v[152:153]
	v_pk_mul_f32 v[154:155], v[62:63], v[154:155]
	v_pk_mul_f32 v[152:153], v[56:57], v[152:153]
	v_pk_mul_f32 v[154:155], v[58:59], v[154:155]
	v_cvt_pk_bf16_f32 v184, v152, v153
	v_cvt_pk_bf16_f32 v185, v154, v155
	global_store_dwordx2 v180, v[184:185], s[64:65]
	v_mul_f32_e32 v152, 0xbfb8aa3b, v52
	v_mul_f32_e32 v153, 0xbfb8aa3b, v53
	v_mul_f32_e32 v154, 0xbfb8aa3b, v54
	v_mul_f32_e32 v155, 0xbfb8aa3b, v55
	v_exp_f32_e32 v152, v152
	v_exp_f32_e32 v153, v153
	v_exp_f32_e32 v154, v154
	v_exp_f32_e32 v155, v155
	v_pk_add_f32 v[152:153], v[152:153], 1.0 op_sel_hi:[1,0]
	v_pk_add_f32 v[154:155], v[154:155], 1.0 op_sel_hi:[1,0]
	v_div_scale_f32 v156, s[38:39], v152, v152, 1.0
	v_div_scale_f32 v157, s[38:39], v153, v153, 1.0
	v_div_scale_f32 v158, s[38:39], v154, v154, 1.0
	v_div_scale_f32 v159, s[38:39], v155, v155, 1.0
	v_rcp_f32_e32 v160, v156
	v_rcp_f32_e32 v161, v157
	v_rcp_f32_e32 v162, v158
	v_rcp_f32_e32 v163, v159
	v_pk_fma_f32 v[164:165], v[156:157], v[160:161], 1.0 op_sel_hi:[1,1,0] neg_lo:[1,0,0] neg_hi:[1,0,0]
	v_pk_fma_f32 v[166:167], v[158:159], v[162:163], 1.0 op_sel_hi:[1,1,0] neg_lo:[1,0,0] neg_hi:[1,0,0]
	v_pk_fma_f32 v[160:161], v[164:165], v[160:161], v[160:161]
	v_pk_fma_f32 v[162:163], v[166:167], v[162:163], v[162:163]
	v_div_scale_f32 v168, s[2:3], 1.0, v152, 1.0
	v_div_scale_f32 v169, s[26:27], 1.0, v153, 1.0
	v_div_scale_f32 v170, s[28:29], 1.0, v154, 1.0
	v_div_scale_f32 v171, vcc, 1.0, v155, 1.0
	v_pk_mul_f32 v[128:129], v[168:169], v[160:161]
	v_pk_mul_f32 v[130:131], v[170:171], v[162:163]
	v_pk_fma_f32 v[164:165], v[156:157], v[128:129], v[168:169] neg_lo:[1,0,0] neg_hi:[1,0,0]
	v_pk_fma_f32 v[166:167], v[158:159], v[130:131], v[170:171] neg_lo:[1,0,0] neg_hi:[1,0,0]
	v_pk_fma_f32 v[128:129], v[164:165], v[160:161], v[128:129]
	v_pk_fma_f32 v[130:131], v[166:167], v[162:163], v[130:131]
	v_pk_fma_f32 v[156:157], v[156:157], v[128:129], v[168:169] neg_lo:[1,0,0] neg_hi:[1,0,0]
	v_pk_fma_f32 v[158:159], v[158:159], v[130:131], v[170:171] neg_lo:[1,0,0] neg_hi:[1,0,0]
	v_div_fmas_f32 v159, v159, v163, v131
	s_mov_b64 vcc, s[28:29]
	v_div_fmas_f32 v158, v158, v162, v130
	s_mov_b64 vcc, s[26:27]
	v_div_fmas_f32 v157, v157, v161, v129
	s_mov_b64 vcc, s[2:3]
	v_div_fmas_f32 v156, v156, v160, v128
	v_div_fixup_f32 v152, v156, v152, 1.0
	v_div_fixup_f32 v153, v157, v153, 1.0
	v_div_fixup_f32 v154, v158, v154, 1.0
	v_div_fixup_f32 v155, v159, v155, 1.0
	v_pk_mul_f32 v[152:153], v[52:53], v[152:153]
	v_pk_mul_f32 v[154:155], v[54:55], v[154:155]
	v_pk_mul_f32 v[152:153], v[48:49], v[152:153]
	v_pk_mul_f32 v[154:155], v[50:51], v[154:155]
	v_cvt_pk_bf16_f32 v186, v152, v153
	v_cvt_pk_bf16_f32 v187, v154, v155
	global_store_dwordx2 v180, v[186:187], s[64:65] offset:128
	v_mul_f32_e32 v152, 0xbfb8aa3b, v44
	v_mul_f32_e32 v153, 0xbfb8aa3b, v45
	v_mul_f32_e32 v154, 0xbfb8aa3b, v46
	v_mul_f32_e32 v155, 0xbfb8aa3b, v47
	v_exp_f32_e32 v152, v152
	v_exp_f32_e32 v153, v153
	v_exp_f32_e32 v154, v154
	v_exp_f32_e32 v155, v155
	v_pk_add_f32 v[152:153], v[152:153], 1.0 op_sel_hi:[1,0]
	v_pk_add_f32 v[154:155], v[154:155], 1.0 op_sel_hi:[1,0]
	v_div_scale_f32 v156, s[38:39], v152, v152, 1.0
	v_div_scale_f32 v157, s[38:39], v153, v153, 1.0
	v_div_scale_f32 v158, s[38:39], v154, v154, 1.0
	v_div_scale_f32 v159, s[38:39], v155, v155, 1.0
	v_rcp_f32_e32 v160, v156
	v_rcp_f32_e32 v161, v157
	v_rcp_f32_e32 v162, v158
	v_rcp_f32_e32 v163, v159
	v_pk_fma_f32 v[164:165], v[156:157], v[160:161], 1.0 op_sel_hi:[1,1,0] neg_lo:[1,0,0] neg_hi:[1,0,0]
	v_pk_fma_f32 v[166:167], v[158:159], v[162:163], 1.0 op_sel_hi:[1,1,0] neg_lo:[1,0,0] neg_hi:[1,0,0]
	v_pk_fma_f32 v[160:161], v[164:165], v[160:161], v[160:161]
	v_pk_fma_f32 v[162:163], v[166:167], v[162:163], v[162:163]
	v_div_scale_f32 v168, s[2:3], 1.0, v152, 1.0
	v_div_scale_f32 v169, s[26:27], 1.0, v153, 1.0
	v_div_scale_f32 v170, s[28:29], 1.0, v154, 1.0
	v_div_scale_f32 v171, vcc, 1.0, v155, 1.0
	v_pk_mul_f32 v[128:129], v[168:169], v[160:161]
	v_pk_mul_f32 v[130:131], v[170:171], v[162:163]
	v_pk_fma_f32 v[164:165], v[156:157], v[128:129], v[168:169] neg_lo:[1,0,0] neg_hi:[1,0,0]
	v_pk_fma_f32 v[166:167], v[158:159], v[130:131], v[170:171] neg_lo:[1,0,0] neg_hi:[1,0,0]
	v_pk_fma_f32 v[128:129], v[164:165], v[160:161], v[128:129]
	v_pk_fma_f32 v[130:131], v[166:167], v[162:163], v[130:131]
	v_pk_fma_f32 v[156:157], v[156:157], v[128:129], v[168:169] neg_lo:[1,0,0] neg_hi:[1,0,0]
	v_pk_fma_f32 v[158:159], v[158:159], v[130:131], v[170:171] neg_lo:[1,0,0] neg_hi:[1,0,0]
	v_div_fmas_f32 v159, v159, v163, v131
	s_mov_b64 vcc, s[28:29]
	v_div_fmas_f32 v158, v158, v162, v130
	s_mov_b64 vcc, s[26:27]
	v_div_fmas_f32 v157, v157, v161, v129
	s_mov_b64 vcc, s[2:3]
	v_div_fmas_f32 v156, v156, v160, v128
	v_div_fixup_f32 v152, v156, v152, 1.0
	v_div_fixup_f32 v153, v157, v153, 1.0
	v_div_fixup_f32 v154, v158, v154, 1.0
	v_div_fixup_f32 v155, v159, v155, 1.0
	v_pk_mul_f32 v[152:153], v[44:45], v[152:153]
	v_pk_mul_f32 v[154:155], v[46:47], v[154:155]
	v_pk_mul_f32 v[152:153], v[40:41], v[152:153]
	v_pk_mul_f32 v[154:155], v[42:43], v[154:155]
	v_cvt_pk_bf16_f32 v184, v152, v153
	v_cvt_pk_bf16_f32 v185, v154, v155
	global_store_dwordx2 v181, v[184:185], s[64:65]
	v_mul_f32_e32 v152, 0xbfb8aa3b, v36
	v_mul_f32_e32 v153, 0xbfb8aa3b, v37
	v_mul_f32_e32 v154, 0xbfb8aa3b, v38
	v_mul_f32_e32 v155, 0xbfb8aa3b, v39
	v_exp_f32_e32 v152, v152
	v_exp_f32_e32 v153, v153
	v_exp_f32_e32 v154, v154
	v_exp_f32_e32 v155, v155
	v_pk_add_f32 v[152:153], v[152:153], 1.0 op_sel_hi:[1,0]
	v_pk_add_f32 v[154:155], v[154:155], 1.0 op_sel_hi:[1,0]
	v_div_scale_f32 v156, s[38:39], v152, v152, 1.0
	v_div_scale_f32 v157, s[38:39], v153, v153, 1.0
	v_div_scale_f32 v158, s[38:39], v154, v154, 1.0
	v_div_scale_f32 v159, s[38:39], v155, v155, 1.0
	v_rcp_f32_e32 v160, v156
	v_rcp_f32_e32 v161, v157
	v_rcp_f32_e32 v162, v158
	v_rcp_f32_e32 v163, v159
	v_pk_fma_f32 v[164:165], v[156:157], v[160:161], 1.0 op_sel_hi:[1,1,0] neg_lo:[1,0,0] neg_hi:[1,0,0]
	v_pk_fma_f32 v[166:167], v[158:159], v[162:163], 1.0 op_sel_hi:[1,1,0] neg_lo:[1,0,0] neg_hi:[1,0,0]
	v_pk_fma_f32 v[160:161], v[164:165], v[160:161], v[160:161]
	v_pk_fma_f32 v[162:163], v[166:167], v[162:163], v[162:163]
	v_div_scale_f32 v168, s[2:3], 1.0, v152, 1.0
	v_div_scale_f32 v169, s[26:27], 1.0, v153, 1.0
	v_div_scale_f32 v170, s[28:29], 1.0, v154, 1.0
	v_div_scale_f32 v171, vcc, 1.0, v155, 1.0
	v_pk_mul_f32 v[128:129], v[168:169], v[160:161]
	v_pk_mul_f32 v[130:131], v[170:171], v[162:163]
	v_pk_fma_f32 v[164:165], v[156:157], v[128:129], v[168:169] neg_lo:[1,0,0] neg_hi:[1,0,0]
	v_pk_fma_f32 v[166:167], v[158:159], v[130:131], v[170:171] neg_lo:[1,0,0] neg_hi:[1,0,0]
	v_pk_fma_f32 v[128:129], v[164:165], v[160:161], v[128:129]
	v_pk_fma_f32 v[130:131], v[166:167], v[162:163], v[130:131]
	v_pk_fma_f32 v[156:157], v[156:157], v[128:129], v[168:169] neg_lo:[1,0,0] neg_hi:[1,0,0]
	v_pk_fma_f32 v[158:159], v[158:159], v[130:131], v[170:171] neg_lo:[1,0,0] neg_hi:[1,0,0]
	v_div_fmas_f32 v159, v159, v163, v131
	s_mov_b64 vcc, s[28:29]
	v_div_fmas_f32 v158, v158, v162, v130
	s_mov_b64 vcc, s[26:27]
	v_div_fmas_f32 v157, v157, v161, v129
	s_mov_b64 vcc, s[2:3]
	v_div_fmas_f32 v156, v156, v160, v128
	v_div_fixup_f32 v152, v156, v152, 1.0
	v_div_fixup_f32 v153, v157, v153, 1.0
	v_div_fixup_f32 v154, v158, v154, 1.0
	v_div_fixup_f32 v155, v159, v155, 1.0
	v_pk_mul_f32 v[152:153], v[36:37], v[152:153]
	v_pk_mul_f32 v[154:155], v[38:39], v[154:155]
	v_pk_mul_f32 v[152:153], v[32:33], v[152:153]
	v_pk_mul_f32 v[154:155], v[34:35], v[154:155]
	v_cvt_pk_bf16_f32 v186, v152, v153
	v_cvt_pk_bf16_f32 v187, v154, v155
	global_store_dwordx2 v181, v[186:187], s[64:65] offset:128
	v_mul_f32_e32 v152, 0xbfb8aa3b, v28
	v_mul_f32_e32 v153, 0xbfb8aa3b, v29
	v_mul_f32_e32 v154, 0xbfb8aa3b, v30
	v_mul_f32_e32 v155, 0xbfb8aa3b, v31
	v_exp_f32_e32 v152, v152
	v_exp_f32_e32 v153, v153
	v_exp_f32_e32 v154, v154
	v_exp_f32_e32 v155, v155
	v_pk_add_f32 v[152:153], v[152:153], 1.0 op_sel_hi:[1,0]
	v_pk_add_f32 v[154:155], v[154:155], 1.0 op_sel_hi:[1,0]
	v_div_scale_f32 v156, s[38:39], v152, v152, 1.0
	v_div_scale_f32 v157, s[38:39], v153, v153, 1.0
	v_div_scale_f32 v158, s[38:39], v154, v154, 1.0
	v_div_scale_f32 v159, s[38:39], v155, v155, 1.0
	v_rcp_f32_e32 v160, v156
	v_rcp_f32_e32 v161, v157
	v_rcp_f32_e32 v162, v158
	v_rcp_f32_e32 v163, v159
	v_pk_fma_f32 v[164:165], v[156:157], v[160:161], 1.0 op_sel_hi:[1,1,0] neg_lo:[1,0,0] neg_hi:[1,0,0]
	v_pk_fma_f32 v[166:167], v[158:159], v[162:163], 1.0 op_sel_hi:[1,1,0] neg_lo:[1,0,0] neg_hi:[1,0,0]
	v_pk_fma_f32 v[160:161], v[164:165], v[160:161], v[160:161]
	v_pk_fma_f32 v[162:163], v[166:167], v[162:163], v[162:163]
	v_div_scale_f32 v168, s[2:3], 1.0, v152, 1.0
	v_div_scale_f32 v169, s[26:27], 1.0, v153, 1.0
	v_div_scale_f32 v170, s[28:29], 1.0, v154, 1.0
	v_div_scale_f32 v171, vcc, 1.0, v155, 1.0
	v_pk_mul_f32 v[128:129], v[168:169], v[160:161]
	v_pk_mul_f32 v[130:131], v[170:171], v[162:163]
	v_pk_fma_f32 v[164:165], v[156:157], v[128:129], v[168:169] neg_lo:[1,0,0] neg_hi:[1,0,0]
	v_pk_fma_f32 v[166:167], v[158:159], v[130:131], v[170:171] neg_lo:[1,0,0] neg_hi:[1,0,0]
	v_pk_fma_f32 v[128:129], v[164:165], v[160:161], v[128:129]
	v_pk_fma_f32 v[130:131], v[166:167], v[162:163], v[130:131]
	v_pk_fma_f32 v[156:157], v[156:157], v[128:129], v[168:169] neg_lo:[1,0,0] neg_hi:[1,0,0]
	v_pk_fma_f32 v[158:159], v[158:159], v[130:131], v[170:171] neg_lo:[1,0,0] neg_hi:[1,0,0]
	v_div_fmas_f32 v159, v159, v163, v131
	s_mov_b64 vcc, s[28:29]
	v_div_fmas_f32 v158, v158, v162, v130
	s_mov_b64 vcc, s[26:27]
	v_div_fmas_f32 v157, v157, v161, v129
	s_mov_b64 vcc, s[2:3]
	v_div_fmas_f32 v156, v156, v160, v128
	v_div_fixup_f32 v152, v156, v152, 1.0
	v_div_fixup_f32 v153, v157, v153, 1.0
	v_div_fixup_f32 v154, v158, v154, 1.0
	v_div_fixup_f32 v155, v159, v155, 1.0
	v_pk_mul_f32 v[152:153], v[28:29], v[152:153]
	v_pk_mul_f32 v[154:155], v[30:31], v[154:155]
	v_pk_mul_f32 v[152:153], v[24:25], v[152:153]
	v_pk_mul_f32 v[154:155], v[26:27], v[154:155]
	v_cvt_pk_bf16_f32 v184, v152, v153
	v_cvt_pk_bf16_f32 v185, v154, v155
	global_store_dwordx2 v182, v[184:185], s[64:65]
	v_mul_f32_e32 v152, 0xbfb8aa3b, v20
	v_mul_f32_e32 v153, 0xbfb8aa3b, v21
	v_mul_f32_e32 v154, 0xbfb8aa3b, v22
	v_mul_f32_e32 v155, 0xbfb8aa3b, v23
	v_exp_f32_e32 v152, v152
	v_exp_f32_e32 v153, v153
	v_exp_f32_e32 v154, v154
	v_exp_f32_e32 v155, v155
	v_pk_add_f32 v[152:153], v[152:153], 1.0 op_sel_hi:[1,0]
	v_pk_add_f32 v[154:155], v[154:155], 1.0 op_sel_hi:[1,0]
	v_div_scale_f32 v156, s[38:39], v152, v152, 1.0
	v_div_scale_f32 v157, s[38:39], v153, v153, 1.0
	v_div_scale_f32 v158, s[38:39], v154, v154, 1.0
	v_div_scale_f32 v159, s[38:39], v155, v155, 1.0
	v_rcp_f32_e32 v160, v156
	v_rcp_f32_e32 v161, v157
	v_rcp_f32_e32 v162, v158
	v_rcp_f32_e32 v163, v159
	v_pk_fma_f32 v[164:165], v[156:157], v[160:161], 1.0 op_sel_hi:[1,1,0] neg_lo:[1,0,0] neg_hi:[1,0,0]
	v_pk_fma_f32 v[166:167], v[158:159], v[162:163], 1.0 op_sel_hi:[1,1,0] neg_lo:[1,0,0] neg_hi:[1,0,0]
	v_pk_fma_f32 v[160:161], v[164:165], v[160:161], v[160:161]
	v_pk_fma_f32 v[162:163], v[166:167], v[162:163], v[162:163]
	v_div_scale_f32 v168, s[2:3], 1.0, v152, 1.0
	v_div_scale_f32 v169, s[26:27], 1.0, v153, 1.0
	v_div_scale_f32 v170, s[28:29], 1.0, v154, 1.0
	v_div_scale_f32 v171, vcc, 1.0, v155, 1.0
	v_pk_mul_f32 v[128:129], v[168:169], v[160:161]
	v_pk_mul_f32 v[130:131], v[170:171], v[162:163]
	v_pk_fma_f32 v[164:165], v[156:157], v[128:129], v[168:169] neg_lo:[1,0,0] neg_hi:[1,0,0]
	v_pk_fma_f32 v[166:167], v[158:159], v[130:131], v[170:171] neg_lo:[1,0,0] neg_hi:[1,0,0]
	v_pk_fma_f32 v[128:129], v[164:165], v[160:161], v[128:129]
	v_pk_fma_f32 v[130:131], v[166:167], v[162:163], v[130:131]
	v_pk_fma_f32 v[156:157], v[156:157], v[128:129], v[168:169] neg_lo:[1,0,0] neg_hi:[1,0,0]
	v_pk_fma_f32 v[158:159], v[158:159], v[130:131], v[170:171] neg_lo:[1,0,0] neg_hi:[1,0,0]
	v_div_fmas_f32 v159, v159, v163, v131
	s_mov_b64 vcc, s[28:29]
	v_div_fmas_f32 v158, v158, v162, v130
	s_mov_b64 vcc, s[26:27]
	v_div_fmas_f32 v157, v157, v161, v129
	s_mov_b64 vcc, s[2:3]
	v_div_fmas_f32 v156, v156, v160, v128
	v_div_fixup_f32 v152, v156, v152, 1.0
	v_div_fixup_f32 v153, v157, v153, 1.0
	v_div_fixup_f32 v154, v158, v154, 1.0
	v_div_fixup_f32 v155, v159, v155, 1.0
	v_pk_mul_f32 v[152:153], v[20:21], v[152:153]
	v_pk_mul_f32 v[154:155], v[22:23], v[154:155]
	v_pk_mul_f32 v[152:153], v[16:17], v[152:153]
	v_pk_mul_f32 v[154:155], v[18:19], v[154:155]
	v_cvt_pk_bf16_f32 v186, v152, v153
	v_cvt_pk_bf16_f32 v187, v154, v155
	global_store_dwordx2 v182, v[186:187], s[64:65] offset:128
	v_mul_f32_e32 v152, 0xbfb8aa3b, v12
	v_mul_f32_e32 v153, 0xbfb8aa3b, v13
	v_mul_f32_e32 v154, 0xbfb8aa3b, v14
	v_mul_f32_e32 v155, 0xbfb8aa3b, v15
	v_exp_f32_e32 v152, v152
	v_exp_f32_e32 v153, v153
	v_exp_f32_e32 v154, v154
	v_exp_f32_e32 v155, v155
	v_pk_add_f32 v[152:153], v[152:153], 1.0 op_sel_hi:[1,0]
	v_pk_add_f32 v[154:155], v[154:155], 1.0 op_sel_hi:[1,0]
	v_div_scale_f32 v156, s[38:39], v152, v152, 1.0
	v_div_scale_f32 v157, s[38:39], v153, v153, 1.0
	v_div_scale_f32 v158, s[38:39], v154, v154, 1.0
	v_div_scale_f32 v159, s[38:39], v155, v155, 1.0
	v_rcp_f32_e32 v160, v156
	v_rcp_f32_e32 v161, v157
	v_rcp_f32_e32 v162, v158
	v_rcp_f32_e32 v163, v159
	v_pk_fma_f32 v[164:165], v[156:157], v[160:161], 1.0 op_sel_hi:[1,1,0] neg_lo:[1,0,0] neg_hi:[1,0,0]
	v_pk_fma_f32 v[166:167], v[158:159], v[162:163], 1.0 op_sel_hi:[1,1,0] neg_lo:[1,0,0] neg_hi:[1,0,0]
	v_pk_fma_f32 v[160:161], v[164:165], v[160:161], v[160:161]
	v_pk_fma_f32 v[162:163], v[166:167], v[162:163], v[162:163]
	v_div_scale_f32 v168, s[2:3], 1.0, v152, 1.0
	v_div_scale_f32 v169, s[26:27], 1.0, v153, 1.0
	v_div_scale_f32 v170, s[28:29], 1.0, v154, 1.0
	v_div_scale_f32 v171, vcc, 1.0, v155, 1.0
	v_pk_mul_f32 v[128:129], v[168:169], v[160:161]
	v_pk_mul_f32 v[130:131], v[170:171], v[162:163]
	v_pk_fma_f32 v[164:165], v[156:157], v[128:129], v[168:169] neg_lo:[1,0,0] neg_hi:[1,0,0]
	v_pk_fma_f32 v[166:167], v[158:159], v[130:131], v[170:171] neg_lo:[1,0,0] neg_hi:[1,0,0]
	v_pk_fma_f32 v[128:129], v[164:165], v[160:161], v[128:129]
	v_pk_fma_f32 v[130:131], v[166:167], v[162:163], v[130:131]
	v_pk_fma_f32 v[156:157], v[156:157], v[128:129], v[168:169] neg_lo:[1,0,0] neg_hi:[1,0,0]
	v_pk_fma_f32 v[158:159], v[158:159], v[130:131], v[170:171] neg_lo:[1,0,0] neg_hi:[1,0,0]
	v_div_fmas_f32 v159, v159, v163, v131
	s_mov_b64 vcc, s[28:29]
	v_div_fmas_f32 v158, v158, v162, v130
	s_mov_b64 vcc, s[26:27]
	v_div_fmas_f32 v157, v157, v161, v129
	s_mov_b64 vcc, s[2:3]
	v_div_fmas_f32 v156, v156, v160, v128
	v_div_fixup_f32 v152, v156, v152, 1.0
	v_div_fixup_f32 v153, v157, v153, 1.0
	v_div_fixup_f32 v154, v158, v154, 1.0
	v_div_fixup_f32 v155, v159, v155, 1.0
	v_pk_mul_f32 v[152:153], v[12:13], v[152:153]
	v_pk_mul_f32 v[154:155], v[14:15], v[154:155]
	v_pk_mul_f32 v[152:153], v[8:9], v[152:153]
	v_pk_mul_f32 v[154:155], v[10:11], v[154:155]
	v_cvt_pk_bf16_f32 v184, v152, v153
	v_cvt_pk_bf16_f32 v185, v154, v155
	global_store_dwordx2 v183, v[184:185], s[64:65]
	v_mul_f32_e32 v152, 0xbfb8aa3b, v4
	v_mul_f32_e32 v153, 0xbfb8aa3b, v5
	v_mul_f32_e32 v154, 0xbfb8aa3b, v6
	v_mul_f32_e32 v155, 0xbfb8aa3b, v7
	v_exp_f32_e32 v152, v152
	v_exp_f32_e32 v153, v153
	v_exp_f32_e32 v154, v154
	v_exp_f32_e32 v155, v155
	v_pk_add_f32 v[152:153], v[152:153], 1.0 op_sel_hi:[1,0]
	v_pk_add_f32 v[154:155], v[154:155], 1.0 op_sel_hi:[1,0]
	v_div_scale_f32 v156, s[38:39], v152, v152, 1.0
	v_div_scale_f32 v157, s[38:39], v153, v153, 1.0
	v_div_scale_f32 v158, s[38:39], v154, v154, 1.0
	v_div_scale_f32 v159, s[38:39], v155, v155, 1.0
	v_rcp_f32_e32 v160, v156
	v_rcp_f32_e32 v161, v157
	v_rcp_f32_e32 v162, v158
	v_rcp_f32_e32 v163, v159
	v_pk_fma_f32 v[164:165], v[156:157], v[160:161], 1.0 op_sel_hi:[1,1,0] neg_lo:[1,0,0] neg_hi:[1,0,0]
	v_pk_fma_f32 v[166:167], v[158:159], v[162:163], 1.0 op_sel_hi:[1,1,0] neg_lo:[1,0,0] neg_hi:[1,0,0]
	v_pk_fma_f32 v[160:161], v[164:165], v[160:161], v[160:161]
	v_pk_fma_f32 v[162:163], v[166:167], v[162:163], v[162:163]
	v_div_scale_f32 v168, s[2:3], 1.0, v152, 1.0
	v_div_scale_f32 v169, s[26:27], 1.0, v153, 1.0
	v_div_scale_f32 v170, s[28:29], 1.0, v154, 1.0
	v_div_scale_f32 v171, vcc, 1.0, v155, 1.0
	v_pk_mul_f32 v[128:129], v[168:169], v[160:161]
	v_pk_mul_f32 v[130:131], v[170:171], v[162:163]
	v_pk_fma_f32 v[164:165], v[156:157], v[128:129], v[168:169] neg_lo:[1,0,0] neg_hi:[1,0,0]
	v_pk_fma_f32 v[166:167], v[158:159], v[130:131], v[170:171] neg_lo:[1,0,0] neg_hi:[1,0,0]
	v_pk_fma_f32 v[128:129], v[164:165], v[160:161], v[128:129]
	v_pk_fma_f32 v[130:131], v[166:167], v[162:163], v[130:131]
	v_pk_fma_f32 v[156:157], v[156:157], v[128:129], v[168:169] neg_lo:[1,0,0] neg_hi:[1,0,0]
	v_pk_fma_f32 v[158:159], v[158:159], v[130:131], v[170:171] neg_lo:[1,0,0] neg_hi:[1,0,0]
	v_div_fmas_f32 v159, v159, v163, v131
	s_mov_b64 vcc, s[28:29]
	v_div_fmas_f32 v158, v158, v162, v130
	s_mov_b64 vcc, s[26:27]
	v_div_fmas_f32 v157, v157, v161, v129
	s_mov_b64 vcc, s[2:3]
	v_div_fmas_f32 v156, v156, v160, v128
	v_div_fixup_f32 v152, v156, v152, 1.0
	v_div_fixup_f32 v153, v157, v153, 1.0
	v_div_fixup_f32 v154, v158, v154, 1.0
	v_div_fixup_f32 v155, v159, v155, 1.0
	v_pk_mul_f32 v[152:153], v[4:5], v[152:153]
	v_pk_mul_f32 v[154:155], v[6:7], v[154:155]
	v_pk_mul_f32 v[152:153], v[0:1], v[152:153]
	v_pk_mul_f32 v[154:155], v[2:3], v[154:155]
	v_cvt_pk_bf16_f32 v186, v152, v153
	v_cvt_pk_bf16_f32 v187, v154, v155
	global_store_dwordx2 v183, v[186:187], s[64:65] offset:128
	s_branch .LBB0_567
